# grid barriers: every block writes back L2 (buffer_wbl2) before arriving, so the XCD leader's release fence finds a clean L2
# baseline (speedup 1.0000x reference)
; __device__ __forceinline__ void xcd_barrier(const XcdBarrier& b) {
;     asm volatile("s_waitcnt vmcnt(0)" ::: "memory");
;     __syncthreads();
;     if (threadIdx.x == 0) {
;         unsigned* bar = b.bar;
;         __builtin_amdgcn_s_waitcnt(0);
;         unsigned nloc = b.st[0], nx = b.st[1];
;         if (nloc == 0u) { xcd_barrier_complete(bar, b.x, nloc, nx); b.st[0] = nloc; b.st[1] = nx; }
.LBB0_180:
	v_readlane_b32 s0, v255, 15
	v_readlane_b32 s16, v252, 18
	s_or_b32 s2, s0, 2
	v_readlane_b32 s23, v252, 25
	s_cmp_ge_i32 s2, s23
	v_readlane_b32 s17, v252, 19
	v_readlane_b32 s18, v252, 20
	v_readlane_b32 s19, v252, 21
	v_readlane_b32 s20, v252, 22
	v_readlane_b32 s21, v252, 23
	v_readlane_b32 s22, v252, 24
	s_cbranch_scc1 .LBB0_230
	s_waitcnt vmcnt(0)
	s_barrier
	s_mov_b64 s[0:1], exec
	v_readlane_b32 s4, v255, 2
	v_readlane_b32 s5, v255, 3
	s_and_b64 s[4:5], s[0:1], s[4:5]
	s_mov_b64 exec, s[4:5]
	s_cbranch_execz .LBB0_229
	v_readlane_b32 s4, v254, 61
	buffer_wbl2 sc1
	s_waitcnt vmcnt(0) expcnt(0) lgkmcnt(0)
	s_nop 0
	v_mov_b32_e32 v0, s4
	ds_read_b32 v3, v0
	v_readlane_b32 s4, v254, 62
	s_waitcnt lgkmcnt(0)
	v_cmp_ne_u32_e32 vcc, 0, v3
	v_mov_b32_e32 v0, s4
	ds_read_b32 v2, v0
	s_cbranch_vccnz .LBB0_197
	v_readlane_b32 s6, v252, 16
	v_readlane_b32 s7, v252, 17
	s_load_dwordx2 s[4:5], s[6:7], 0x4
	s_mov_b32 s7, 1
	s_waitcnt lgkmcnt(0)
	s_mul_i32 s6, s4, s3
	s_mul_i32 s6, s6, s5
	s_branch .LBB0_185

; __device__ __forceinline__ void xcd_barrier(const XcdBarrier& b) {
;     asm volatile("s_waitcnt vmcnt(0)" ::: "memory");
;     __syncthreads();
;     if (threadIdx.x == 0) {
;         unsigned* bar = b.bar;
;         __builtin_amdgcn_s_waitcnt(0);
;         unsigned nloc = b.st[0], nx = b.st[1];
;         if (nloc == 0u) { xcd_barrier_complete(bar, b.x, nloc, nx); b.st[0] = nloc; b.st[1] = nx; }
.LBB0_280:
	v_readlane_b32 s0, v255, 15
	v_readlane_b32 s16, v252, 18
	s_or_b32 s2, s0, 3
	v_readlane_b32 s23, v252, 25
	s_cmp_ge_i32 s2, s23
	v_readlane_b32 s17, v252, 19
	v_readlane_b32 s18, v252, 20
	v_readlane_b32 s19, v252, 21
	v_readlane_b32 s20, v252, 22
	v_readlane_b32 s21, v252, 23
	v_readlane_b32 s22, v252, 24
	s_cbranch_scc1 .LBB0_330
	s_waitcnt vmcnt(0)
	s_waitcnt lgkmcnt(0)
	s_barrier
	s_mov_b64 s[0:1], exec
	v_readlane_b32 s6, v255, 2
	v_readlane_b32 s7, v255, 3
	s_and_b64 s[6:7], s[0:1], s[6:7]
	s_mov_b64 exec, s[6:7]
	s_cbranch_execz .LBB0_329
	v_readlane_b32 s6, v254, 61
	buffer_wbl2 sc1
	s_waitcnt vmcnt(0) expcnt(0) lgkmcnt(0)
	s_nop 0
	v_mov_b32_e32 v0, s6
	ds_read_b32 v3, v0
	v_readlane_b32 s6, v254, 62
	s_waitcnt lgkmcnt(0)
	v_cmp_ne_u32_e32 vcc, 0, v3
	v_mov_b32_e32 v0, s6
	ds_read_b32 v2, v0
	s_cbranch_vccnz .LBB0_297
	v_readlane_b32 s8, v252, 16
	v_readlane_b32 s9, v252, 17
	s_load_dwordx2 s[6:7], s[8:9], 0x4
	s_waitcnt lgkmcnt(0)
	s_mul_i32 s6, s6, s3
	s_mul_i32 s6, s6, s7
	s_mov_b32 s7, 1
	s_branch .LBB0_285

; __device__ __forceinline__ void xcd_barrier(const XcdBarrier& b) {
;     asm volatile("s_waitcnt vmcnt(0)" ::: "memory");
;     __syncthreads();
;     if (threadIdx.x == 0) {
;         unsigned* bar = b.bar;
;         __builtin_amdgcn_s_waitcnt(0);
;         unsigned nloc = b.st[0], nx = b.st[1];
;         if (nloc == 0u) { xcd_barrier_complete(bar, b.x, nloc, nx); b.st[0] = nloc; b.st[1] = nx; }
.LBB0_386:
	v_readlane_b32 s0, v255, 15
	v_readlane_b32 s16, v252, 18
	s_or_b32 s0, s0, 4
	v_readlane_b32 s23, v252, 25
	v_readlane_b32 s22, v252, 24
	s_cmp_ge_i32 s0, s23
	v_readlane_b32 s42, v255, 6
	v_readlane_b32 s17, v252, 19
	v_readlane_b32 s18, v252, 20
	v_readlane_b32 s19, v252, 21
	v_readlane_b32 s20, v252, 22
	v_readlane_b32 s21, v252, 23
	v_readlane_b32 s43, v255, 7
	s_cbranch_scc1 .LBB0_436
	s_waitcnt vmcnt(0)
	s_waitcnt lgkmcnt(0)
	s_barrier
	s_mov_b64 s[0:1], exec
	v_readlane_b32 s4, v255, 2
	v_readlane_b32 s5, v255, 3
	s_and_b64 s[4:5], s[0:1], s[4:5]
	s_mov_b64 exec, s[4:5]
	s_cbranch_execz .LBB0_435
	v_readlane_b32 s2, v254, 61
	buffer_wbl2 sc1
	s_waitcnt vmcnt(0) expcnt(0) lgkmcnt(0)
	s_nop 0
	v_mov_b32_e32 v0, s2
	ds_read_b32 v3, v0
	v_readlane_b32 s2, v254, 62
	s_waitcnt lgkmcnt(0)
	v_cmp_ne_u32_e32 vcc, 0, v3
	v_mov_b32_e32 v0, s2
	ds_read_b32 v2, v0
	s_cbranch_vccnz .LBB0_403
	v_readlane_b32 s6, v252, 16
	v_readlane_b32 s7, v252, 17
	s_load_dwordx2 s[4:5], s[6:7], 0x4
	s_mov_b32 s6, 1
	s_waitcnt lgkmcnt(0)
	s_mul_i32 s2, s4, s3
	s_mul_i32 s2, s2, s5
	s_branch .LBB0_391

; __device__ __forceinline__ void xcd_barrier(const XcdBarrier& b) {
;     asm volatile("s_waitcnt vmcnt(0)" ::: "memory");
;     __syncthreads();
;     if (threadIdx.x == 0) {
;         unsigned* bar = b.bar;
;         __builtin_amdgcn_s_waitcnt(0);
;         unsigned nloc = b.st[0], nx = b.st[1];
;         if (nloc == 0u) { xcd_barrier_complete(bar, b.x, nloc, nx); b.st[0] = nloc; b.st[1] = nx; }
.LBB0_758:
	v_readlane_b32 s0, v255, 15
	v_readlane_b32 s16, v252, 18
	s_or_b32 s2, s0, 6
	v_readlane_b32 s23, v252, 25
	s_cmp_ge_i32 s2, s23
	v_readlane_b32 s17, v252, 19
	v_readlane_b32 s18, v252, 20
	v_readlane_b32 s19, v252, 21
	v_readlane_b32 s20, v252, 22
	v_readlane_b32 s21, v252, 23
	v_readlane_b32 s22, v252, 24
	s_cbranch_scc1 .LBB0_770
	s_waitcnt vmcnt(0)
	s_barrier
	s_mov_b64 s[0:1], exec
	v_readlane_b32 s4, v255, 2
	v_readlane_b32 s5, v255, 3
	v_readlane_b32 s54, v255, 23
	s_and_b64 s[4:5], s[0:1], s[4:5]
	v_readlane_b32 s57, v255, 11
	v_readlane_b32 s58, v255, 12
	v_readlane_b32 s52, v255, 13
	s_movk_i32 s59, 0x2c00
	v_readlane_b32 s55, v255, 24
	v_readlane_b32 s53, v255, 14
	s_mov_b64 exec, s[4:5]
	s_cbranch_execz .LBB0_808
	v_readlane_b32 s4, v254, 61
	buffer_wbl2 sc1
	s_waitcnt vmcnt(0) expcnt(0) lgkmcnt(0)
	s_nop 0
	v_mov_b32_e32 v0, s4
	ds_read_b32 v3, v0
	v_readlane_b32 s4, v254, 62
	s_waitcnt lgkmcnt(0)
	v_cmp_ne_u32_e32 vcc, 0, v3
	v_mov_b32_e32 v0, s4
	ds_read_b32 v2, v0
	s_cbranch_vccnz .LBB0_776
	v_readlane_b32 s6, v252, 16
	v_readlane_b32 s7, v252, 17
	s_load_dwordx2 s[4:5], s[6:7], 0x4
	s_mov_b32 s7, 1
	s_waitcnt lgkmcnt(0)
	s_mul_i32 s6, s4, s3
	s_mul_i32 s6, s6, s5
	s_branch .LBB0_763

; __device__ __forceinline__ void xcd_barrier(const XcdBarrier& b) {
;     asm volatile("s_waitcnt vmcnt(0)" ::: "memory");
;     __syncthreads();
;     if (threadIdx.x == 0) {
;         unsigned* bar = b.bar;
;         __builtin_amdgcn_s_waitcnt(0);
;         unsigned nloc = b.st[0], nx = b.st[1];
;         if (nloc == 0u) { xcd_barrier_complete(bar, b.x, nloc, nx); b.st[0] = nloc; b.st[1] = nx; }
.LBB0_856:
	v_readlane_b32 s2, v255, 15
	v_readlane_b32 s16, v252, 18
	s_or_b32 s2, s2, 7
	v_readlane_b32 s23, v252, 25
	s_cmp_ge_i32 s2, s23
	v_readlane_b32 s17, v252, 19
	v_readlane_b32 s18, v252, 20
	v_readlane_b32 s19, v252, 21
	v_readlane_b32 s20, v252, 22
	v_readlane_b32 s21, v252, 23
	v_readlane_b32 s22, v252, 24
	s_cbranch_scc1 .LBB0_906
	s_waitcnt vmcnt(0)
	s_waitcnt lgkmcnt(0)
	s_barrier
	s_mov_b64 s[4:5], exec
	v_readlane_b32 s6, v255, 2
	v_readlane_b32 s7, v255, 3
	s_and_b64 s[6:7], s[4:5], s[6:7]
	s_mov_b64 exec, s[6:7]
	s_cbranch_execz .LBB0_905
	v_readlane_b32 s6, v254, 61
	buffer_wbl2 sc1
	s_waitcnt vmcnt(0) expcnt(0) lgkmcnt(0)
	s_nop 0
	v_mov_b32_e32 v0, s6
	ds_read_b32 v3, v0
	v_readlane_b32 s6, v254, 62
	s_waitcnt lgkmcnt(0)
	v_cmp_ne_u32_e32 vcc, 0, v3
	v_mov_b32_e32 v0, s6
	ds_read_b32 v2, v0
	s_cbranch_vccnz .LBB0_873
	v_readlane_b32 s8, v252, 16
	v_readlane_b32 s9, v252, 17
	s_load_dwordx2 s[6:7], s[8:9], 0x4
	s_waitcnt lgkmcnt(0)
	s_mul_i32 s6, s6, s3
	s_mul_i32 s6, s6, s7
	s_mov_b32 s7, 1
	s_branch .LBB0_861

; __device__ __forceinline__ void xcd_barrier(const XcdBarrier& b) {
;     asm volatile("s_waitcnt vmcnt(0)" ::: "memory");
;     __syncthreads();
;     if (threadIdx.x == 0) {
;         unsigned* bar = b.bar;
;         __builtin_amdgcn_s_waitcnt(0);
;         unsigned nloc = b.st[0], nx = b.st[1];
;         if (nloc == 0u) { xcd_barrier_complete(bar, b.x, nloc, nx); b.st[0] = nloc; b.st[1] = nx; }
.LBB0_931:
	v_readlane_b32 s0, v255, 15
	v_readlane_b32 s16, v252, 18
	s_add_i32 s2, s0, 8
	v_readlane_b32 s23, v252, 25
	s_cmp_ge_i32 s2, s23
	v_readlane_b32 s17, v252, 19
	v_readlane_b32 s18, v252, 20
	v_readlane_b32 s19, v252, 21
	v_readlane_b32 s20, v252, 22
	v_readlane_b32 s21, v252, 23
	v_readlane_b32 s22, v252, 24
	s_cbranch_scc1 .LBB0_981
	s_waitcnt vmcnt(0)
	s_barrier
	s_mov_b64 s[0:1], exec
	v_readlane_b32 s4, v255, 2
	v_readlane_b32 s5, v255, 3
	s_and_b64 s[4:5], s[0:1], s[4:5]
	s_mov_b64 exec, s[4:5]
	s_cbranch_execz .LBB0_980
	v_readlane_b32 s4, v254, 61
	buffer_wbl2 sc1
	s_waitcnt vmcnt(0) expcnt(0) lgkmcnt(0)
	s_nop 0
	v_mov_b32_e32 v0, s4
	ds_read_b32 v3, v0
	v_readlane_b32 s4, v254, 62
	s_waitcnt lgkmcnt(0)
	v_cmp_ne_u32_e32 vcc, 0, v3
	v_mov_b32_e32 v0, s4
	ds_read_b32 v2, v0
	s_cbranch_vccnz .LBB0_948
	v_readlane_b32 s6, v252, 16
	v_readlane_b32 s7, v252, 17
	s_load_dwordx2 s[4:5], s[6:7], 0x4
	s_mov_b32 s7, 1
	s_waitcnt lgkmcnt(0)
	s_mul_i32 s6, s4, s3
	s_mul_i32 s6, s6, s5
	s_branch .LBB0_936

; __device__ __forceinline__ void xcd_barrier(const XcdBarrier& b) {
;     ...
;     if (threadIdx.x == 0) {
;         unsigned* bar = b.bar;
;         __builtin_amdgcn_s_waitcnt(0);
;         unsigned nloc = b.st[0], nx = b.st[1];
;         if (nloc == 0u) { xcd_barrier_complete(bar, b.x, nloc, nx); b.st[0] = nloc; b.st[1] = nx; }
.LBB0_1032:
	v_readlane_b32 s2, v254, 61
	buffer_wbl2 sc1
	s_waitcnt vmcnt(0) expcnt(0) lgkmcnt(0)
	s_nop 0
	v_mov_b32_e32 v0, s2
	ds_read_b32 v3, v0
	v_readlane_b32 s2, v254, 62
	s_waitcnt lgkmcnt(0)
	v_cmp_ne_u32_e32 vcc, 0, v3
	v_mov_b32_e32 v0, s2
	ds_read_b32 v2, v0
	s_cbranch_vccnz .LBB0_1047
	v_readlane_b32 s6, v252, 16
	v_readlane_b32 s7, v252, 17
	s_load_dwordx2 s[4:5], s[6:7], 0x4
	s_mov_b32 s6, 1
	s_waitcnt lgkmcnt(0)
	s_mul_i32 s2, s4, s3
	s_mul_i32 s2, s2, s5
	s_branch .LBB0_1035
